# accumulator zero-init with 64-bit literal-zero moves (half the VALU issue slots per unit)
# speedup vs baseline: 1.0038x; 1.0038x over previous
.LBB0_215:
	s_ashr_i32 s13, s12, 31
	s_lshl_b64 s[16:17], s[12:13], 21
	s_add_u32 s16, s70, s16
	s_addc_u32 s17, s71, s17
	s_and_b64 s[18:19], s[2:3], exec
	s_cselect_b32 s13, s17, s1
	s_cselect_b32 s24, s16, s0
	s_ashr_i32 s15, s14, 31
	s_lshl_b64 s[18:19], s[14:15], 21
	s_add_u32 s18, s6, s18
	s_addc_u32 s19, s7, s19
	s_and_b64 s[22:23], s[2:3], exec
	s_cselect_b32 s15, s19, s21
	s_cselect_b32 s25, s18, s20
	s_add_u32 s0, s0, 0x100080
	s_addc_u32 s1, s1, 0
	s_add_u32 s27, s20, 0x100
	v_mov_b32_e32 v2, 0
	s_addc_u32 s29, s21, 0
	s_mov_b32 s30, -2
	v_mov_b64_e32 v[2:3], 0
	v_mov_b64_e32 v[4:5], 0
	v_mov_b64_e32 v[6:7], 0
	v_mov_b64_e32 v[8:9], 0
	v_mov_b64_e32 v[10:11], 0
	v_mov_b64_e32 v[12:13], 0
	v_mov_b64_e32 v[14:15], 0
	v_mov_b64_e32 v[16:17], 0
	v_mov_b64_e32 v[18:19], 0
	v_mov_b64_e32 v[20:21], 0
	v_mov_b64_e32 v[22:23], 0
	v_mov_b64_e32 v[24:25], 0
	v_mov_b64_e32 v[26:27], 0
	v_mov_b64_e32 v[28:29], 0
	v_mov_b64_e32 v[30:31], 0
	v_mov_b64_e32 v[32:33], 0
	v_mov_b64_e32 v[34:35], 0
	v_mov_b64_e32 v[36:37], 0
	v_mov_b64_e32 v[38:39], 0
	v_mov_b64_e32 v[40:41], 0
	v_mov_b64_e32 v[42:43], 0
	v_mov_b64_e32 v[44:45], 0
	v_mov_b64_e32 v[46:47], 0
	v_mov_b64_e32 v[48:49], 0
	v_mov_b64_e32 v[50:51], 0
	v_mov_b64_e32 v[52:53], 0
	v_mov_b64_e32 v[54:55], 0
	v_mov_b64_e32 v[56:57], 0
	v_mov_b64_e32 v[58:59], 0
	v_mov_b64_e32 v[60:61], 0
	v_mov_b64_e32 v[62:63], 0
	v_mov_b64_e32 v[64:65], 0
	v_mov_b64_e32 v[66:67], 0
	v_mov_b64_e32 v[68:69], 0
	v_mov_b64_e32 v[70:71], 0
	v_mov_b64_e32 v[72:73], 0
	v_mov_b64_e32 v[74:75], 0
	v_mov_b64_e32 v[76:77], 0
	v_mov_b64_e32 v[78:79], 0
	v_mov_b64_e32 v[80:81], 0
	v_mov_b64_e32 v[82:83], 0
	v_mov_b64_e32 v[84:85], 0
	v_mov_b64_e32 v[86:87], 0
	v_mov_b64_e32 v[88:89], 0
	v_mov_b64_e32 v[90:91], 0
	v_mov_b64_e32 v[92:93], 0
	v_mov_b64_e32 v[94:95], 0
	v_mov_b64_e32 v[96:97], 0
	v_mov_b64_e32 v[98:99], 0
	v_mov_b64_e32 v[100:101], 0
	v_mov_b64_e32 v[102:103], 0
	v_mov_b64_e32 v[104:105], 0
	v_mov_b64_e32 v[106:107], 0
	v_mov_b64_e32 v[108:109], 0
	v_mov_b64_e32 v[110:111], 0
	v_mov_b64_e32 v[112:113], 0
	v_mov_b64_e32 v[114:115], 0
	v_mov_b64_e32 v[116:117], 0
	v_mov_b64_e32 v[118:119], 0
	v_mov_b64_e32 v[120:121], 0
	v_mov_b64_e32 v[122:123], 0
	v_mov_b64_e32 v[124:125], 0
	v_mov_b64_e32 v[126:127], 0
	v_mov_b64_e32 v[128:129], 0
	v_add_u32_e32 v246, 0x18000, v158
	v_add_u32_e32 v247, 0x1c000, v158

.LBB0_270:
	s_ashr_i32 s13, s12, 31
	s_lshl_b64 s[14:15], s[12:13], 20
	s_add_u32 s14, s79, s14
	s_addc_u32 s15, s93, s15
	s_and_b64 s[16:17], s[2:3], exec
	s_cselect_b32 s13, s15, s21
	s_cselect_b32 s25, s14, s20
	s_ashr_i32 s11, s10, 31
	s_lshl_b64 s[16:17], s[10:11], 20
	s_add_u32 s16, s76, s16
	s_addc_u32 s17, s77, s17
	s_and_b64 s[22:23], s[2:3], exec
	s_cselect_b32 s11, s17, s1
	s_cselect_b32 s26, s16, s0
	s_add_u32 s20, s20, 0x80080
	s_addc_u32 s21, s21, 0
	s_add_u32 s27, s0, 0x100
	v_mov_b32_e32 v34, 0
	v_mov_b32_e32 v173, v163
	v_mov_b32_e32 v169, v163
	v_mov_b32_e32 v171, v163
	s_addc_u32 s28, s1, 0
	s_mov_b32 s29, -2
	v_mov_b64_e32 v[34:35], 0
	v_mov_b64_e32 v[36:37], 0
	v_mov_b64_e32 v[38:39], 0
	v_mov_b64_e32 v[40:41], 0
	v_mov_b64_e32 v[42:43], 0
	v_mov_b64_e32 v[44:45], 0
	v_mov_b64_e32 v[46:47], 0
	v_mov_b64_e32 v[48:49], 0
	v_mov_b64_e32 v[50:51], 0
	v_mov_b64_e32 v[52:53], 0
	v_mov_b64_e32 v[54:55], 0
	v_mov_b64_e32 v[56:57], 0
	v_mov_b64_e32 v[58:59], 0
	v_mov_b64_e32 v[60:61], 0
	v_mov_b64_e32 v[62:63], 0
	v_mov_b64_e32 v[64:65], 0
	v_mov_b64_e32 v[66:67], 0
	v_mov_b64_e32 v[68:69], 0
	v_mov_b64_e32 v[70:71], 0
	v_mov_b64_e32 v[72:73], 0
	v_mov_b64_e32 v[74:75], 0
	v_mov_b64_e32 v[76:77], 0
	v_mov_b64_e32 v[78:79], 0
	v_mov_b64_e32 v[80:81], 0
	v_mov_b64_e32 v[82:83], 0
	v_mov_b64_e32 v[84:85], 0
	v_mov_b64_e32 v[86:87], 0
	v_mov_b64_e32 v[88:89], 0
	v_mov_b64_e32 v[90:91], 0
	v_mov_b64_e32 v[92:93], 0
	v_mov_b64_e32 v[94:95], 0
	v_mov_b64_e32 v[96:97], 0
	v_mov_b64_e32 v[98:99], 0
	v_mov_b64_e32 v[100:101], 0
	v_mov_b64_e32 v[102:103], 0
	v_mov_b64_e32 v[104:105], 0
	v_mov_b64_e32 v[106:107], 0
	v_mov_b64_e32 v[108:109], 0
	v_mov_b64_e32 v[110:111], 0
	v_mov_b64_e32 v[112:113], 0
	v_mov_b64_e32 v[114:115], 0
	v_mov_b64_e32 v[116:117], 0
	v_mov_b64_e32 v[118:119], 0
	v_mov_b64_e32 v[120:121], 0
	v_mov_b64_e32 v[122:123], 0
	v_mov_b64_e32 v[124:125], 0
	v_mov_b64_e32 v[126:127], 0
	v_mov_b64_e32 v[128:129], 0
	v_mov_b64_e32 v[130:131], 0
	v_mov_b64_e32 v[132:133], 0
	v_mov_b64_e32 v[134:135], 0
	v_mov_b64_e32 v[136:137], 0
	v_mov_b64_e32 v[138:139], 0
	v_mov_b64_e32 v[140:141], 0
	v_mov_b64_e32 v[142:143], 0
	v_mov_b64_e32 v[144:145], 0
	v_mov_b64_e32 v[146:147], 0
	v_mov_b64_e32 v[148:149], 0
	v_mov_b64_e32 v[150:151], 0
	v_mov_b64_e32 v[152:153], 0
	v_mov_b64_e32 v[154:155], 0
	v_mov_b64_e32 v[156:157], 0
	v_mov_b64_e32 v[158:159], 0
	v_mov_b64_e32 v[160:161], 0
	v_add_u32_e32 v246, 0x18000, v182
	v_add_u32_e32 v247, 0x1c000, v182

.LBB0_838:
	s_ashr_i32 s21, s20, 31
	s_lshl_b64 s[22:23], s[20:21], 19
	s_add_u32 s22, s68, s22
	s_addc_u32 s23, s69, s23
	s_and_b64 s[24:25], s[2:3], exec
	s_cselect_b32 s21, s23, s29
	s_cselect_b32 s49, s22, s28
	s_ashr_i32 s19, s18, 31
	s_lshl_b64 s[24:25], s[18:19], 19
	v_readlane_b32 s34, v245, 14
	v_readlane_b32 s35, v245, 15
	s_add_u32 s24, s34, s24
	s_addc_u32 s25, s35, s25
	s_and_b64 s[34:35], s[2:3], exec
	s_cselect_b32 s19, s25, s31
	s_cselect_b32 s50, s24, s30
	s_add_u32 s28, s28, 0x40080
	s_addc_u32 s29, s29, 0
	s_add_u32 s51, s30, 0x100
	v_mov_b32_e32 v34, 0
	v_mov_b32_e32 v173, v163
	v_mov_b32_e32 v169, v163
	v_mov_b32_e32 v171, v163
	s_addc_u32 s52, s31, 0
	s_mov_b32 s53, -2
	v_mov_b64_e32 v[34:35], 0
	v_mov_b64_e32 v[36:37], 0
	v_mov_b64_e32 v[38:39], 0
	v_mov_b64_e32 v[40:41], 0
	v_mov_b64_e32 v[42:43], 0
	v_mov_b64_e32 v[44:45], 0
	v_mov_b64_e32 v[46:47], 0
	v_mov_b64_e32 v[48:49], 0
	v_mov_b64_e32 v[50:51], 0
	v_mov_b64_e32 v[52:53], 0
	v_mov_b64_e32 v[54:55], 0
	v_mov_b64_e32 v[56:57], 0
	v_mov_b64_e32 v[58:59], 0
	v_mov_b64_e32 v[60:61], 0
	v_mov_b64_e32 v[62:63], 0
	v_mov_b64_e32 v[64:65], 0
	v_mov_b64_e32 v[66:67], 0
	v_mov_b64_e32 v[68:69], 0
	v_mov_b64_e32 v[70:71], 0
	v_mov_b64_e32 v[72:73], 0
	v_mov_b64_e32 v[74:75], 0
	v_mov_b64_e32 v[76:77], 0
	v_mov_b64_e32 v[78:79], 0
	v_mov_b64_e32 v[80:81], 0
	v_mov_b64_e32 v[82:83], 0
	v_mov_b64_e32 v[84:85], 0
	v_mov_b64_e32 v[86:87], 0
	v_mov_b64_e32 v[88:89], 0
	v_mov_b64_e32 v[90:91], 0
	v_mov_b64_e32 v[92:93], 0
	v_mov_b64_e32 v[94:95], 0
	v_mov_b64_e32 v[96:97], 0
	s_waitcnt vmcnt(0)
	v_mov_b64_e32 v[98:99], 0
	v_mov_b64_e32 v[100:101], 0
	v_mov_b64_e32 v[102:103], 0
	v_mov_b64_e32 v[104:105], 0
	v_mov_b64_e32 v[106:107], 0
	v_mov_b64_e32 v[108:109], 0
	v_mov_b64_e32 v[110:111], 0
	v_mov_b64_e32 v[112:113], 0
	v_mov_b64_e32 v[114:115], 0
	v_mov_b64_e32 v[116:117], 0
	v_mov_b64_e32 v[118:119], 0
	v_mov_b64_e32 v[120:121], 0
	v_mov_b64_e32 v[122:123], 0
	v_mov_b64_e32 v[124:125], 0
	v_mov_b64_e32 v[126:127], 0
	v_mov_b64_e32 v[128:129], 0
	v_mov_b64_e32 v[130:131], 0
	v_mov_b64_e32 v[132:133], 0
	v_mov_b64_e32 v[134:135], 0
	v_mov_b64_e32 v[136:137], 0
	v_mov_b64_e32 v[138:139], 0
	v_mov_b64_e32 v[140:141], 0
	v_mov_b64_e32 v[142:143], 0
	v_mov_b64_e32 v[144:145], 0
	v_mov_b64_e32 v[146:147], 0
	v_mov_b64_e32 v[148:149], 0
	v_mov_b64_e32 v[150:151], 0
	v_mov_b64_e32 v[152:153], 0
	v_mov_b64_e32 v[154:155], 0
	v_mov_b64_e32 v[156:157], 0
	v_mov_b64_e32 v[158:159], 0
	v_mov_b64_e32 v[160:161], 0
	v_add_u32_e32 v246, 0x18000, v182
	v_add_u32_e32 v247, 0x1c000, v182

.LBB0_862:
	s_ashr_i32 s13, s12, 31
	s_lshl_b64 s[14:15], s[12:13], 20
	s_add_u32 s14, s62, s14
	s_addc_u32 s15, s63, s15
	s_and_b64 s[16:17], s[2:3], exec
	s_cselect_b32 s13, s15, s21
	s_cselect_b32 s39, s14, s20
	s_ashr_i32 s11, s10, 31
	s_lshl_b64 s[16:17], s[10:11], 20
	v_readlane_b32 s24, v245, 16
	v_readlane_b32 s25, v245, 17
	s_add_u32 s16, s24, s16
	s_addc_u32 s17, s25, s17
	s_and_b64 s[24:25], s[2:3], exec
	s_cselect_b32 s11, s17, s23
	s_cselect_b32 s40, s16, s22
	s_add_u32 s20, s20, 0x80080
	s_addc_u32 s21, s21, 0
	s_add_u32 s41, s22, 0x100
	v_mov_b32_e32 v2, 0
	s_addc_u32 s42, s23, 0
	s_mov_b32 s43, -2
	v_mov_b64_e32 v[2:3], 0
	v_mov_b64_e32 v[4:5], 0
	v_mov_b64_e32 v[6:7], 0
	v_mov_b64_e32 v[8:9], 0
	v_mov_b64_e32 v[10:11], 0
	v_mov_b64_e32 v[12:13], 0
	v_mov_b64_e32 v[14:15], 0
	v_mov_b64_e32 v[16:17], 0
	v_mov_b64_e32 v[18:19], 0
	v_mov_b64_e32 v[20:21], 0
	v_mov_b64_e32 v[22:23], 0
	v_mov_b64_e32 v[24:25], 0
	v_mov_b64_e32 v[26:27], 0
	v_mov_b64_e32 v[28:29], 0
	v_mov_b64_e32 v[30:31], 0
	v_mov_b64_e32 v[32:33], 0
	v_mov_b64_e32 v[34:35], 0
	v_mov_b64_e32 v[36:37], 0
	v_mov_b64_e32 v[38:39], 0
	v_mov_b64_e32 v[40:41], 0
	v_mov_b64_e32 v[42:43], 0
	v_mov_b64_e32 v[44:45], 0
	v_mov_b64_e32 v[46:47], 0
	v_mov_b64_e32 v[48:49], 0
	v_mov_b64_e32 v[50:51], 0
	v_mov_b64_e32 v[52:53], 0
	v_mov_b64_e32 v[54:55], 0
	v_mov_b64_e32 v[56:57], 0
	v_mov_b64_e32 v[58:59], 0
	v_mov_b64_e32 v[60:61], 0
	v_mov_b64_e32 v[62:63], 0
	v_mov_b64_e32 v[64:65], 0
	v_mov_b64_e32 v[66:67], 0
	v_mov_b64_e32 v[68:69], 0
	v_mov_b64_e32 v[70:71], 0
	v_mov_b64_e32 v[72:73], 0
	v_mov_b64_e32 v[74:75], 0
	v_mov_b64_e32 v[76:77], 0
	v_mov_b64_e32 v[78:79], 0
	v_mov_b64_e32 v[80:81], 0
	v_mov_b64_e32 v[82:83], 0
	v_mov_b64_e32 v[84:85], 0
	v_mov_b64_e32 v[86:87], 0
	v_mov_b64_e32 v[88:89], 0
	v_mov_b64_e32 v[90:91], 0
	v_mov_b64_e32 v[92:93], 0
	v_mov_b64_e32 v[94:95], 0
	v_mov_b64_e32 v[96:97], 0
	v_mov_b64_e32 v[98:99], 0
	v_mov_b64_e32 v[100:101], 0
	v_mov_b64_e32 v[102:103], 0
	v_mov_b64_e32 v[104:105], 0
	v_mov_b64_e32 v[106:107], 0
	v_mov_b64_e32 v[108:109], 0
	v_mov_b64_e32 v[110:111], 0
	v_mov_b64_e32 v[112:113], 0
	v_mov_b64_e32 v[114:115], 0
	v_mov_b64_e32 v[116:117], 0
	v_mov_b64_e32 v[118:119], 0
	v_mov_b64_e32 v[120:121], 0
	v_mov_b64_e32 v[122:123], 0
	v_mov_b64_e32 v[124:125], 0
	v_mov_b64_e32 v[126:127], 0
	v_mov_b64_e32 v[128:129], 0
	v_add_u32_e32 v246, 0x18000, v152
	v_add_u32_e32 v247, 0x1c000, v152

.LBB0_940:
	s_ashr_i32 s21, s20, 31
	s_lshl_b64 s[22:23], s[20:21], 21
	s_add_u32 s22, s0, s22
	s_addc_u32 s23, s1, s23
	s_and_b64 s[24:25], s[4:5], exec
	s_cselect_b32 s21, s23, s29
	s_cselect_b32 s27, s22, s28
	s_ashr_i32 s19, s18, 31
	s_lshl_b64 s[24:25], s[18:19], 21
	v_readlane_b32 s34, v245, 18
	v_readlane_b32 s35, v245, 19
	s_add_u32 s24, s34, s24
	s_addc_u32 s25, s35, s25
	s_and_b64 s[34:35], s[4:5], exec
	s_cselect_b32 s19, s25, s31
	s_cselect_b32 s48, s24, s30
	s_add_u32 s28, s28, 0x100080
	s_addc_u32 s29, s29, 0
	s_add_u32 s49, s30, 0x100
	v_mov_b32_e32 v2, 0
	s_addc_u32 s50, s31, 0
	s_mov_b32 s51, -2
	s_waitcnt lgkmcnt(0)
	v_mov_b64_e32 v[2:3], 0
	v_mov_b64_e32 v[4:5], 0
	v_mov_b64_e32 v[6:7], 0
	v_mov_b64_e32 v[8:9], 0
	v_mov_b64_e32 v[10:11], 0
	v_mov_b64_e32 v[12:13], 0
	v_mov_b64_e32 v[14:15], 0
	v_mov_b64_e32 v[16:17], 0
	v_mov_b64_e32 v[18:19], 0
	v_mov_b64_e32 v[20:21], 0
	v_mov_b64_e32 v[22:23], 0
	v_mov_b64_e32 v[24:25], 0
	v_mov_b64_e32 v[26:27], 0
	v_mov_b64_e32 v[28:29], 0
	v_mov_b64_e32 v[30:31], 0
	v_mov_b64_e32 v[32:33], 0
	v_mov_b64_e32 v[34:35], 0
	v_mov_b64_e32 v[36:37], 0
	v_mov_b64_e32 v[38:39], 0
	v_mov_b64_e32 v[40:41], 0
	v_mov_b64_e32 v[42:43], 0
	v_mov_b64_e32 v[44:45], 0
	v_mov_b64_e32 v[46:47], 0
	v_mov_b64_e32 v[48:49], 0
	v_mov_b64_e32 v[50:51], 0
	v_mov_b64_e32 v[52:53], 0
	v_mov_b64_e32 v[54:55], 0
	v_mov_b64_e32 v[56:57], 0
	v_mov_b64_e32 v[58:59], 0
	v_mov_b64_e32 v[60:61], 0
	v_mov_b64_e32 v[62:63], 0
	v_mov_b64_e32 v[64:65], 0
	v_mov_b64_e32 v[66:67], 0
	v_mov_b64_e32 v[68:69], 0
	v_mov_b64_e32 v[70:71], 0
	v_mov_b64_e32 v[72:73], 0
	v_mov_b64_e32 v[82:83], 0
	v_mov_b64_e32 v[84:85], 0
	v_mov_b64_e32 v[86:87], 0
	v_mov_b64_e32 v[88:89], 0
	s_waitcnt vmcnt(0)
	v_mov_b64_e32 v[74:75], 0
	v_mov_b64_e32 v[76:77], 0
	v_mov_b64_e32 v[78:79], 0
	v_mov_b64_e32 v[80:81], 0
	v_mov_b64_e32 v[98:99], 0
	v_mov_b64_e32 v[100:101], 0
	v_mov_b64_e32 v[106:107], 0
	v_mov_b64_e32 v[108:109], 0
	v_mov_b64_e32 v[114:115], 0
	v_mov_b64_e32 v[116:117], 0
	v_mov_b64_e32 v[118:119], 0
	v_mov_b64_e32 v[120:121], 0
	v_mov_b64_e32 v[122:123], 0
	v_mov_b64_e32 v[124:125], 0
	v_mov_b64_e32 v[126:127], 0
	v_mov_b64_e32 v[128:129], 0
	v_mov_b64_e32 v[130:131], 0
	v_mov_b64_e32 v[132:133], 0
	v_mov_b64_e32 v[134:135], 0
	v_mov_b64_e32 v[136:137], 0
	v_mov_b64_e32 v[138:139], 0
	v_mov_b64_e32 v[140:141], 0
	v_mov_b64_e32 v[142:143], 0
	v_mov_b64_e32 v[144:145], 0
	v_add_u32_e32 v246, 0x18000, v186
	v_add_u32_e32 v247, 0x1c000, v186

.LBB0_1133:
	v_lshrrev_b32_e32 v19, 1, v10
	v_and_b32_e32 v19, 24, v19
	v_and_b32_e32 v186, 15, v10
	v_lshlrev_b32_e32 v20, 1, v19
	v_lshlrev_b32_e32 v10, 2, v10
	s_lshl_b32 s4, s6, 13
	v_lshl_or_b32 v20, v186, 6, v20
	v_and_b32_e32 v10, 32, v10
	v_bitop3_b32 v21, v20, s4, v10 bitop3:0xde
	s_lshl_b32 s4, s62, 5
	s_mov_b64 s[34:35], 0x80
	s_and_b32 s7, s4, 0x60
	s_add_i32 m0, s64, 0x18000
	v_lshl_add_u64 v[8:9], v[8:9], 0, s[34:35]
	s_lshl_b32 s69, s6, 6
	s_lshl_b32 s4, s7, 7
	s_waitcnt vmcnt(2)
	s_barrier
	global_load_lds_dwordx4 v[8:9], off
	v_lshl_add_u64 v[6:7], v[6:7], 0, s[34:35]
	s_add_i32 m0, s64, 0x1a000
	s_add_i32 s74, s64, 0x8000
	s_add_i32 s75, s64, 0xa000
	v_bitop3_b32 v187, v20, s4, v10 bitop3:0xde
	global_load_lds_dwordx4 v[6:7], off
	v_lshl_add_u64 v[4:5], v[4:5], 0, s[34:35]
	s_mov_b32 m0, s74
	s_add_u32 s4, s56, 0x100080
	global_load_lds_dwordx4 v[4:5], off
	v_lshl_add_u64 v[2:3], v[2:3], 0, s[34:35]
	s_mov_b32 m0, s75
	s_addc_u32 s5, s57, 0
	global_load_lds_dwordx4 v[2:3], off
	s_add_i32 m0, s64, 0x1c000
	v_lshl_add_u64 v[2:3], s[4:5], 0, v[180:181]
	global_load_lds_dwordx4 v[2:3], off
	v_lshl_add_u64 v[2:3], s[4:5], 0, v[184:185]
	s_add_i32 m0, s64, 0x1e000
	s_cmpk_lt_u32 s38, 0x100
	global_load_lds_dwordx4 v[2:3], off
	s_cselect_b64 s[36:37], -1, 0
	s_cmpk_gt_u32 s38, 0xff
	s_cselect_b64 s[38:39], -1, 0
	s_lshl_b32 s6, s6, 10
	v_lshl_add_u32 v2, v186, 9, s6
	v_add_u32_e32 v4, 0xffffe400, v2
	v_sub_u32_e64 v2, v186, 14 clamp
	v_or_b32_e32 v3, s9, v2
	v_or_b32_e32 v2, s8, v2
	v_or_b32_e32 v224, s7, v19
	v_lshlrev_b32_e32 v5, 9, v3
	v_lshlrev_b32_e32 v6, 9, v2
	v_lshlrev_b32_e32 v2, 4, v11
	v_mov_b32_e32 v3, v181
	s_lshl_b32 s29, s61, 5
	v_lshrrev_b32_e32 v7, 5, v11
	v_lshl_add_u64 v[190:191], s[40:41], 0, v[2:3]
	s_add_i32 s92, s33, s29
	s_add_i32 s29, 0, 0x20000
	v_lshlrev_b32_e32 v2, 2, v224
	s_add_i32 s33, 0, 0x20800
	v_add3_u32 v226, s29, v4, v2
	v_add3_u32 v227, s33, v4, v2
	v_add3_u32 v228, s29, v5, v2
	v_add3_u32 v229, s29, v6, v2
	v_mul_u32_u24_e32 v2, 0x2b00, v7
	v_readlane_b32 s76, v245, 52
	v_lshlrev_b32_e32 v2, 2, v2
	v_readlane_b32 s90, v244, 2
	v_readlane_b32 s91, v244, 3
	v_lshl_add_u64 v[194:195], s[10:11], 0, v[2:3]
	s_mov_b64 s[42:43], 0x100080
	v_lshl_add_u64 v[192:193], s[90:91], 0, v[2:3]
	v_lshlrev_b32_e32 v2, 16, v13
	v_and_b32_e32 v2, 0xfffe0000, v2
	v_lshl_add_u32 v2, v14, 13, v2
	v_and_b32_e32 v3, 1, v13
	v_lshl_or_b32 v2, v3, 6, v2
	v_lshl_add_u32 v2, v15, 1, v2
	v_mov_b32_e32 v3, v181
	v_lshl_add_u64 v[196:197], v[2:3], 0, s[42:43]
	v_lshlrev_b32_e32 v2, 16, v16
	v_and_b32_e32 v2, 0xfffe0000, v2
	v_lshl_add_u32 v2, v17, 13, v2
	v_and_b32_e32 v3, 1, v16
	s_waitcnt vmcnt(6)
	v_lshl_or_b32 v2, v3, 6, v2
	v_cmp_lt_u32_e32 vcc, 1, v186
	v_readlane_b32 s77, v245, 53
	v_readlane_b32 s78, v245, 54
	v_readlane_b32 s79, v245, 55
	v_readlane_b32 s80, v245, 56
	v_readlane_b32 s81, v245, 57
	v_readlane_b32 s88, v244, 0
	v_lshl_add_u32 v2, v18, 1, v2
	v_mov_b32_e32 v3, v181
	v_or_b32_e32 v1, s69, v186
	v_cmp_lt_u32_e64 s[4:5], 13, v186
	v_add_u32_e32 v188, -14, v186
	v_mov_b32_e32 v189, v181
	s_or_b64 s[38:39], s[38:39], vcc
	v_cmp_eq_u32_e64 s[6:7], 15, v186
	v_and_b32_e32 v225, 0x7c, v12
	v_cmp_lt_u32_e64 s[8:9], 31, v11
	s_add_i32 s41, s64, 0x21000
	v_lshl_add_u64 v[198:199], v[2:3], 0, s[42:43]
	s_movk_i32 s77, 0x2b1
	s_add_i32 s78, 0, 0x10000
	s_add_i32 s79, 0, 0x14000
	v_add_u32_e32 v230, 0, v21
	s_mov_b32 s80, 0xac00
	s_mov_b32 s40, 0x3dd2d3e8
	s_movk_i32 s81, 0x5600
	v_mov_b64_e32 v[200:201], 0x1580
	v_mov_b32_e32 v231, 0xac00
	v_mov_b32_e32 v2, 0
	v_mov_b64_e32 v[4:5], 0
	v_mov_b64_e32 v[6:7], 0
	v_mov_b64_e32 v[8:9], 0
	v_mov_b64_e32 v[10:11], 0
	v_mov_b64_e32 v[12:13], 0
	v_mov_b64_e32 v[14:15], 0
	v_mov_b64_e32 v[16:17], 0
	v_mov_b64_e32 v[18:19], 0
	v_mov_b64_e32 v[20:21], 0
	v_mov_b64_e32 v[22:23], 0
	v_mov_b64_e32 v[24:25], 0
	v_mov_b64_e32 v[26:27], 0
	v_mov_b64_e32 v[28:29], 0
	v_mov_b64_e32 v[30:31], 0
	v_mov_b64_e32 v[32:33], 0
	v_mov_b64_e32 v[34:35], 0
	v_mov_b64_e32 v[36:37], 0
	v_mov_b64_e32 v[38:39], 0
	v_mov_b64_e32 v[40:41], 0
	v_mov_b64_e32 v[42:43], 0
	v_mov_b64_e32 v[44:45], 0
	v_mov_b64_e32 v[46:47], 0
	v_mov_b64_e32 v[48:49], 0
	v_mov_b64_e32 v[50:51], 0
	v_mov_b64_e32 v[52:53], 0
	v_mov_b64_e32 v[54:55], 0
	v_mov_b64_e32 v[56:57], 0
	v_mov_b64_e32 v[58:59], 0
	v_mov_b64_e32 v[60:61], 0
	v_mov_b64_e32 v[62:63], 0
	v_mov_b64_e32 v[64:65], 0
	v_mov_b64_e32 v[66:67], 0
	v_mov_b64_e32 v[68:69], 0
	v_mov_b64_e32 v[70:71], 0
	v_mov_b64_e32 v[72:73], 0
	v_mov_b64_e32 v[74:75], 0
	v_mov_b64_e32 v[76:77], 0
	v_mov_b64_e32 v[78:79], 0
	v_mov_b64_e32 v[80:81], 0
	v_mov_b64_e32 v[82:83], 0
	v_mov_b64_e32 v[84:85], 0
	v_mov_b64_e32 v[86:87], 0
	v_mov_b64_e32 v[88:89], 0
	v_mov_b64_e32 v[90:91], 0
	v_mov_b64_e32 v[92:93], 0
	v_mov_b64_e32 v[94:95], 0
	v_mov_b64_e32 v[96:97], 0
	v_mov_b64_e32 v[98:99], 0
	v_mov_b64_e32 v[100:101], 0
	v_mov_b64_e32 v[102:103], 0
	v_mov_b64_e32 v[104:105], 0
	v_mov_b64_e32 v[106:107], 0
	v_mov_b64_e32 v[108:109], 0
	v_mov_b64_e32 v[110:111], 0
	v_mov_b64_e32 v[112:113], 0
	v_mov_b64_e32 v[114:115], 0
	v_mov_b64_e32 v[116:117], 0
	v_mov_b64_e32 v[118:119], 0
	v_mov_b64_e32 v[120:121], 0
	v_mov_b64_e32 v[122:123], 0
	v_mov_b64_e32 v[124:125], 0
	v_mov_b64_e32 v[126:127], 0
	v_mov_b64_e32 v[128:129], 0
	s_mov_b64 s[90:91], s[20:21]
	s_mov_b32 s88, s22
	s_barrier
	v_readlane_b32 s82, v245, 58
	v_readlane_b32 s83, v245, 59
	v_readlane_b32 s84, v245, 60
	v_readlane_b32 s85, v245, 61
	v_readlane_b32 s86, v245, 62
	v_readlane_b32 s87, v245, 63
	v_readlane_b32 s89, v244, 1
	s_branch .LBB0_1136
.LBB0_1134:
	v_mov_b32_e32 v5, 0
	v_mov_b64_e32 v[2:3], 0
	v_mov_b64_e32 v[4:5], 0
	v_mov_b64_e32 v[6:7], 0
	v_mov_b64_e32 v[8:9], 0
	v_mov_b64_e32 v[10:11], 0
	v_mov_b64_e32 v[12:13], 0
	v_mov_b64_e32 v[14:15], 0
	v_mov_b64_e32 v[16:17], 0
	v_mov_b64_e32 v[18:19], 0
	v_mov_b64_e32 v[20:21], 0
	v_mov_b64_e32 v[22:23], 0
	v_mov_b64_e32 v[24:25], 0
	v_mov_b64_e32 v[26:27], 0
	v_mov_b64_e32 v[28:29], 0
	v_mov_b64_e32 v[30:31], 0
	v_mov_b64_e32 v[32:33], 0
	v_mov_b64_e32 v[34:35], 0
	v_mov_b64_e32 v[36:37], 0
	v_mov_b64_e32 v[38:39], 0
	v_mov_b64_e32 v[40:41], 0
	v_mov_b64_e32 v[42:43], 0
	v_mov_b64_e32 v[44:45], 0
	v_mov_b64_e32 v[46:47], 0
	v_mov_b64_e32 v[48:49], 0
	v_mov_b64_e32 v[50:51], 0
	v_mov_b64_e32 v[52:53], 0
	v_mov_b64_e32 v[54:55], 0
	v_mov_b64_e32 v[56:57], 0
	v_mov_b64_e32 v[58:59], 0
	v_mov_b64_e32 v[60:61], 0
	v_mov_b64_e32 v[62:63], 0
	v_mov_b64_e32 v[64:65], 0
	v_mov_b64_e32 v[66:67], 0
	v_mov_b64_e32 v[68:69], 0
	v_mov_b64_e32 v[70:71], 0
	v_mov_b64_e32 v[72:73], 0
	v_mov_b64_e32 v[74:75], 0
	v_mov_b64_e32 v[76:77], 0
	v_mov_b64_e32 v[78:79], 0
	v_mov_b64_e32 v[80:81], 0
	v_mov_b64_e32 v[82:83], 0
	v_mov_b64_e32 v[84:85], 0
	v_mov_b64_e32 v[86:87], 0
	v_mov_b64_e32 v[88:89], 0
	v_mov_b64_e32 v[90:91], 0
	v_mov_b64_e32 v[92:93], 0
	v_mov_b64_e32 v[94:95], 0
	v_mov_b64_e32 v[96:97], 0
	v_mov_b64_e32 v[98:99], 0
	v_mov_b64_e32 v[100:101], 0
	v_mov_b64_e32 v[102:103], 0
	v_mov_b64_e32 v[104:105], 0
	v_mov_b64_e32 v[106:107], 0
	v_mov_b64_e32 v[108:109], 0
	v_mov_b64_e32 v[110:111], 0
	v_mov_b64_e32 v[112:113], 0
	v_mov_b64_e32 v[114:115], 0
	v_mov_b64_e32 v[116:117], 0
	v_mov_b64_e32 v[118:119], 0
	v_mov_b64_e32 v[120:121], 0
	v_mov_b64_e32 v[122:123], 0
	v_mov_b64_e32 v[124:125], 0
	v_mov_b64_e32 v[126:127], 0
	v_mov_b64_e32 v[128:129], 0
	s_mov_b32 s28, s44
	s_mov_b32 s30, s42

.LBB0_1324:
	s_add_u32 s24, s24, 0x2b0080
	s_addc_u32 s25, s25, 0
	s_add_u32 s47, s26, 0x100
	v_mov_b32_e32 v2, 0
	s_addc_u32 s48, s27, 0
	s_mov_b32 s49, -2
	v_mov_b64_e32 v[2:3], 0
	v_mov_b64_e32 v[4:5], 0
	v_mov_b64_e32 v[6:7], 0
	v_mov_b64_e32 v[8:9], 0
	v_mov_b64_e32 v[10:11], 0
	v_mov_b64_e32 v[12:13], 0
	v_mov_b64_e32 v[14:15], 0
	v_mov_b64_e32 v[16:17], 0
	v_mov_b64_e32 v[18:19], 0
	v_mov_b64_e32 v[20:21], 0
	v_mov_b64_e32 v[22:23], 0
	v_mov_b64_e32 v[24:25], 0
	v_mov_b64_e32 v[26:27], 0
	v_mov_b64_e32 v[28:29], 0
	v_mov_b64_e32 v[30:31], 0
	v_mov_b64_e32 v[32:33], 0
	v_mov_b64_e32 v[34:35], 0
	v_mov_b64_e32 v[36:37], 0
	v_mov_b64_e32 v[38:39], 0
	v_mov_b64_e32 v[40:41], 0
	v_mov_b64_e32 v[42:43], 0
	v_mov_b64_e32 v[44:45], 0
	v_mov_b64_e32 v[46:47], 0
	v_mov_b64_e32 v[48:49], 0
	v_mov_b64_e32 v[50:51], 0
	v_mov_b64_e32 v[52:53], 0
	v_mov_b64_e32 v[54:55], 0
	v_mov_b64_e32 v[56:57], 0
	v_mov_b64_e32 v[58:59], 0
	v_mov_b64_e32 v[60:61], 0
	v_mov_b64_e32 v[62:63], 0
	v_mov_b64_e32 v[64:65], 0
	v_mov_b64_e32 v[66:67], 0
	v_mov_b64_e32 v[68:69], 0
	v_mov_b64_e32 v[70:71], 0
	v_mov_b64_e32 v[72:73], 0
	v_mov_b64_e32 v[82:83], 0
	v_mov_b64_e32 v[84:85], 0
	v_mov_b64_e32 v[86:87], 0
	v_mov_b64_e32 v[88:89], 0
	s_waitcnt vmcnt(0)
	v_mov_b64_e32 v[74:75], 0
	v_mov_b64_e32 v[76:77], 0
	v_mov_b64_e32 v[78:79], 0
	v_mov_b64_e32 v[80:81], 0
	v_mov_b64_e32 v[90:91], 0
	v_mov_b64_e32 v[92:93], 0
	v_mov_b64_e32 v[94:95], 0
	v_mov_b64_e32 v[96:97], 0
	v_mov_b64_e32 v[98:99], 0
	v_mov_b64_e32 v[100:101], 0
	v_mov_b64_e32 v[102:103], 0
	v_mov_b64_e32 v[104:105], 0
	v_mov_b64_e32 v[106:107], 0
	v_mov_b64_e32 v[108:109], 0
	v_mov_b64_e32 v[110:111], 0
	v_mov_b64_e32 v[112:113], 0
	v_mov_b64_e32 v[114:115], 0
	v_mov_b64_e32 v[116:117], 0
	v_mov_b64_e32 v[118:119], 0
	v_mov_b64_e32 v[120:121], 0
	v_mov_b64_e32 v[122:123], 0
	v_mov_b64_e32 v[124:125], 0
	v_mov_b64_e32 v[126:127], 0
	v_mov_b64_e32 v[128:129], 0
	v_add_u32_e32 v246, 0x18000, v174
	v_add_u32_e32 v247, 0x1c000, v174
